# up rstd LDS table on top of dpp fusion (silu packing dropped: it measured no gain)
# baseline (speedup 1.0000x reference)
.LBB0_408:
	s_or_b64 exec, exec, s[38:39]
	s_mov_b32 s4, 0x358637bd
	v_mov_b64_e32 v[214:215], s[4:5]
	s_mov_b64 s[26:27], -1
	v_pk_mul_f32 v[16:17], v[16:17], v[240:241] op_sel_hi:[1,0]
	v_pk_mul_f32 v[220:221], v[68:69], v[242:243] op_sel_hi:[1,0]
	v_pk_mul_f32 v[218:219], v[66:67], v[242:243] op_sel_hi:[1,0]
	v_pk_mul_f32 v[216:217], v[72:73], v[240:241] op_sel_hi:[1,0]
	v_pk_mul_f32 v[72:73], v[64:65], v[236:237] op_sel_hi:[1,0]
	s_waitcnt vmcnt(3)
	v_pk_mul_f32 v[64:65], v[154:155], v[198:199]
	v_pk_mul_f32 v[68:69], v[60:61], v[238:239] op_sel_hi:[1,0]
	v_pk_mul_f32 v[60:61], v[178:179], v[198:199]
	v_pk_mul_f32 v[66:67], v[58:59], v[238:239] op_sel_hi:[1,0]
	v_pk_mul_f32 v[58:59], v[180:181], v[200:201]
	v_pk_fma_f32 v[60:61], v[154:155], v[194:195], v[60:61]
	v_pk_mul_f32 v[214:215], v[70:71], v[240:241] op_sel_hi:[1,0]
	v_pk_mul_f32 v[70:71], v[62:63], v[236:237] op_sel_hi:[1,0]
	v_pk_fma_f32 v[58:59], v[156:157], v[196:197], v[58:59]
	v_pk_fma_f32 v[60:61], v[66:67], v[190:191], v[60:61]
	v_pk_mul_f32 v[62:63], v[156:157], v[200:201]
	v_pk_fma_f32 v[64:65], v[66:67], v[194:195], v[64:65]
	v_pk_mul_f32 v[66:67], v[66:67], v[198:199]
	v_pk_fma_f32 v[58:59], v[68:69], v[192:193], v[58:59]
	v_pk_fma_f32 v[62:63], v[68:69], v[196:197], v[62:63]
	v_pk_fma_f32 v[64:65], v[70:71], v[190:191], v[64:65]
	v_pk_mul_f32 v[68:69], v[68:69], v[200:201]
	v_pk_fma_f32 v[154:155], v[70:71], v[194:195], v[66:67]
	v_pk_mul_f32 v[70:71], v[70:71], v[198:199]
	v_pk_fma_f32 v[62:63], v[72:73], v[192:193], v[62:63]
	v_pk_fma_f32 v[66:67], v[72:73], v[196:197], v[68:69]
	v_pk_fma_f32 v[68:69], v[218:219], v[190:191], v[154:155]
	v_pk_mul_f32 v[72:73], v[72:73], v[200:201]
	v_pk_fma_f32 v[154:155], v[218:219], v[194:195], v[70:71]
	v_pk_fma_f32 v[70:71], v[220:221], v[196:197], v[72:73]
	v_pk_fma_f32 v[72:73], v[214:215], v[190:191], v[154:155]
	v_pk_mul_f32 v[154:155], v[220:221], v[200:201]
	v_pk_mul_f32 v[156:157], v[218:219], v[198:199]
	v_pk_fma_f32 v[154:155], v[216:217], v[196:197], v[154:155]
	v_pk_fma_f32 v[156:157], v[214:215], v[194:195], v[156:157]
	v_pk_mul_f32 v[178:179], v[216:217], v[200:201]
	v_pk_mul_f32 v[180:181], v[214:215], v[198:199]
	v_pk_fma_f32 v[154:155], v[128:129], v[192:193], v[154:155]
	v_pk_fma_f32 v[156:157], v[126:127], v[190:191], v[156:157]
	v_pk_fma_f32 v[180:181], v[126:127], v[194:195], v[180:181]
	v_pk_fma_f32 v[178:179], v[128:129], v[196:197], v[178:179]
	v_pk_mul_f32 v[128:129], v[128:129], v[200:201]
	v_pk_mul_f32 v[126:127], v[126:127], v[198:199]
	v_pk_fma_f32 v[128:129], v[124:125], v[196:197], v[128:129]
	v_pk_fma_f32 v[214:215], v[122:123], v[194:195], v[126:127]
	s_waitcnt lgkmcnt(0)
	v_pk_mul_f32 v[196:197], v[196:197], v[204:205]
	v_pk_mul_f32 v[194:195], v[194:195], v[202:203]
	v_pk_fma_f32 v[178:179], v[124:125], v[192:193], v[178:179]
	v_pk_fma_f32 v[124:125], v[124:125], v[200:201], v[196:197]
	v_pk_fma_f32 v[194:195], v[122:123], v[198:199], v[194:195]
	v_pk_mul_f32 v[198:199], v[38:39], v[236:237] op_sel_hi:[1,0]
	v_pk_mul_f32 v[200:201], v[40:41], v[236:237] op_sel_hi:[1,0]
	v_pk_mul_f32 v[38:39], v[144:145], v[176:177]
	v_pk_mul_f32 v[40:41], v[142:143], v[174:175]
	v_pk_mul_f32 v[34:35], v[34:35], v[238:239] op_sel_hi:[1,0]
	v_pk_mul_f32 v[36:37], v[36:37], v[238:239] op_sel_hi:[1,0]
	v_pk_fma_f32 v[38:39], v[136:137], v[164:165], v[38:39]
	v_pk_fma_f32 v[40:41], v[134:135], v[162:163], v[40:41]
	v_pk_fma_f32 v[66:67], v[220:221], v[192:193], v[66:67]
	v_pk_fma_f32 v[70:71], v[216:217], v[192:193], v[70:71]
	v_pk_fma_f32 v[180:181], v[122:123], v[190:191], v[180:181]
	v_pk_fma_f32 v[126:127], v[192:193], v[204:205], v[128:129]
	v_pk_fma_f32 v[128:129], v[190:191], v[202:203], v[214:215]
	v_pk_fma_f32 v[122:123], v[192:193], v[208:209], v[124:125]
	v_pk_fma_f32 v[124:125], v[190:191], v[206:207], v[194:195]
	v_pk_mul_f32 v[190:191], v[54:55], v[240:241] op_sel_hi:[1,0]
	v_pk_mul_f32 v[192:193], v[56:57], v[240:241] op_sel_hi:[1,0]
	v_pk_fma_f32 v[56:57], v[36:37], v[160:161], v[38:39]
	v_pk_fma_f32 v[54:55], v[34:35], v[158:159], v[40:41]
	v_pk_mul_f32 v[38:39], v[136:137], v[176:177]
	v_pk_mul_f32 v[40:41], v[134:135], v[174:175]
	v_pk_fma_f32 v[38:39], v[36:37], v[164:165], v[38:39]
	v_pk_fma_f32 v[40:41], v[34:35], v[162:163], v[40:41]
	v_pk_mul_f32 v[36:37], v[36:37], v[176:177]
	v_pk_mul_f32 v[34:35], v[34:35], v[174:175]
	v_pk_mul_f32 v[194:195], v[50:51], v[242:243] op_sel_hi:[1,0]
	v_pk_mul_f32 v[196:197], v[52:53], v[242:243] op_sel_hi:[1,0]
	v_pk_fma_f32 v[34:35], v[198:199], v[162:163], v[34:35]
	v_pk_fma_f32 v[36:37], v[200:201], v[164:165], v[36:37]
	v_pk_fma_f32 v[52:53], v[200:201], v[160:161], v[38:39]
	v_pk_fma_f32 v[50:51], v[198:199], v[158:159], v[40:41]
	v_pk_fma_f32 v[40:41], v[196:197], v[160:161], v[36:37]
	v_pk_fma_f32 v[38:39], v[194:195], v[158:159], v[34:35]
	v_pk_mul_f32 v[34:35], v[200:201], v[176:177]
	v_pk_mul_f32 v[36:37], v[198:199], v[174:175]
	v_pk_fma_f32 v[34:35], v[196:197], v[164:165], v[34:35]
	v_pk_fma_f32 v[134:135], v[194:195], v[162:163], v[36:37]
	v_pk_mul_f32 v[136:137], v[194:195], v[174:175]
	v_pk_fma_f32 v[36:37], v[192:193], v[160:161], v[34:35]
	v_pk_fma_f32 v[34:35], v[190:191], v[158:159], v[134:135]
	v_pk_mul_f32 v[134:135], v[196:197], v[176:177]
	v_pk_fma_f32 v[136:137], v[190:191], v[162:163], v[136:137]
	v_pk_mul_f32 v[144:145], v[190:191], v[174:175]
	v_pk_fma_f32 v[134:135], v[192:193], v[164:165], v[134:135]
	v_pk_fma_f32 v[136:137], v[118:119], v[158:159], v[136:137]
	v_pk_mul_f32 v[142:143], v[192:193], v[176:177]
	v_pk_fma_f32 v[144:145], v[118:119], v[162:163], v[144:145]
	v_pk_mul_f32 v[118:119], v[118:119], v[174:175]
	v_pk_fma_f32 v[134:135], v[120:121], v[160:161], v[134:135]
	v_pk_fma_f32 v[142:143], v[120:121], v[164:165], v[142:143]
	v_pk_mul_f32 v[120:121], v[120:121], v[176:177]
	v_pk_fma_f32 v[118:119], v[114:115], v[162:163], v[118:119]
	v_pk_fma_f32 v[120:121], v[116:117], v[164:165], v[120:121]
	v_pk_fma_f32 v[192:193], v[158:159], v[182:183], v[118:119]
	v_pk_mul_f32 v[118:119], v[164:165], v[184:185]
	v_pk_mul_f32 v[164:165], v[30:31], v[240:241] op_sel_hi:[1,0]
	v_pk_mul_f32 v[30:31], v[132:133], v[152:153]
	v_pk_fma_f32 v[142:143], v[116:117], v[160:161], v[142:143]
	v_pk_fma_f32 v[116:117], v[116:117], v[176:177], v[118:119]
	v_pk_mul_f32 v[20:21], v[20:21], v[238:239] op_sel_hi:[1,0]
	v_pk_fma_f32 v[30:31], v[104:105], v[148:149], v[30:31]
	v_pk_fma_f32 v[190:191], v[160:161], v[184:185], v[120:121]
	v_pk_fma_f32 v[160:161], v[160:161], v[188:189], v[116:117]
	v_pk_fma_f32 v[116:117], v[20:21], v[140:141], v[30:31]
	v_pk_mul_f32 v[30:31], v[104:105], v[152:153]
	v_pk_mul_f32 v[120:121], v[162:163], v[182:183]
	v_pk_mul_f32 v[162:163], v[32:33], v[240:241] op_sel_hi:[1,0]
	v_pk_mul_f32 v[24:25], v[24:25], v[236:237] op_sel_hi:[1,0]
	v_pk_mul_f32 v[32:33], v[130:131], v[150:151]
	v_pk_fma_f32 v[30:31], v[20:21], v[148:149], v[30:31]
	v_pk_mul_f32 v[20:21], v[20:21], v[152:153]
	v_pk_fma_f32 v[144:145], v[114:115], v[158:159], v[144:145]
	v_pk_fma_f32 v[114:115], v[114:115], v[174:175], v[120:121]
	v_pk_mul_f32 v[28:29], v[28:29], v[242:243] op_sel_hi:[1,0]
	v_pk_mul_f32 v[18:19], v[18:19], v[238:239] op_sel_hi:[1,0]
	v_pk_fma_f32 v[32:33], v[102:103], v[146:147], v[32:33]
	v_pk_fma_f32 v[20:21], v[24:25], v[148:149], v[20:21]
	v_pk_fma_f32 v[158:159], v[158:159], v[186:187], v[114:115]
	v_pk_fma_f32 v[114:115], v[18:19], v[138:139], v[32:33]
	v_pk_mul_f32 v[32:33], v[102:103], v[150:151]
	v_pk_fma_f32 v[120:121], v[28:29], v[140:141], v[20:21]
	v_pk_mul_f32 v[20:21], v[24:25], v[152:153]
	v_pk_mul_f32 v[22:23], v[22:23], v[236:237] op_sel_hi:[1,0]
	v_pk_fma_f32 v[32:33], v[18:19], v[146:147], v[32:33]
	v_pk_mul_f32 v[18:19], v[18:19], v[150:151]
	v_pk_fma_f32 v[20:21], v[28:29], v[148:149], v[20:21]
	v_pk_mul_f32 v[26:27], v[26:27], v[242:243] op_sel_hi:[1,0]
	v_pk_fma_f32 v[18:19], v[22:23], v[146:147], v[18:19]
	v_pk_fma_f32 v[132:133], v[162:163], v[140:141], v[20:21]
	v_pk_mul_f32 v[20:21], v[28:29], v[152:153]
	v_pk_fma_f32 v[118:119], v[26:27], v[138:139], v[18:19]
	v_pk_mul_f32 v[18:19], v[22:23], v[150:151]
	v_pk_fma_f32 v[20:21], v[162:163], v[148:149], v[20:21]
	v_pk_fma_f32 v[102:103], v[22:23], v[138:139], v[32:33]
	v_pk_fma_f32 v[18:19], v[26:27], v[146:147], v[18:19]
	v_pk_fma_f32 v[32:33], v[112:113], v[140:141], v[20:21]
	v_pk_mul_f32 v[20:21], v[162:163], v[152:153]
	v_pk_fma_f32 v[130:131], v[164:165], v[138:139], v[18:19]
	v_pk_mul_f32 v[18:19], v[26:27], v[150:151]
	v_pk_fma_f32 v[20:21], v[112:113], v[148:149], v[20:21]
	v_pk_fma_f32 v[18:19], v[164:165], v[146:147], v[18:19]
	v_pk_fma_f32 v[28:29], v[108:109], v[140:141], v[20:21]
	v_pk_mul_f32 v[20:21], v[110:111], v[150:151]
	v_pk_fma_f32 v[104:105], v[24:25], v[140:141], v[30:31]
	v_pk_fma_f32 v[30:31], v[110:111], v[138:139], v[18:19]
	v_pk_mul_f32 v[18:19], v[164:165], v[150:151]
	v_pk_fma_f32 v[20:21], v[106:107], v[146:147], v[20:21]
	v_pk_fma_f32 v[18:19], v[110:111], v[146:147], v[18:19]
	v_pk_fma_f32 v[24:25], v[138:139], v[166:167], v[20:21]
	v_pk_mul_f32 v[20:21], v[146:147], v[166:167]
	v_pk_fma_f32 v[26:27], v[106:107], v[138:139], v[18:19]
	v_pk_fma_f32 v[20:21], v[106:107], v[150:151], v[20:21]
	v_mul_f32_e32 v106, 0xbfb8aa3b, v158
	v_mul_f32_e32 v107, 0xbfb8aa3b, v159
	v_exp_f32_e32 v106, v106
	v_exp_f32_e32 v107, v107
	v_pk_mul_f32 v[18:19], v[112:113], v[152:153]
	v_pk_fma_f32 v[20:21], v[138:139], v[170:171], v[20:21]
	v_pk_fma_f32 v[18:19], v[108:109], v[148:149], v[18:19]
	v_add_f32_e32 v106, 1.0, v106
	v_add_f32_e32 v107, 1.0, v107
	v_pk_fma_f32 v[22:23], v[140:141], v[168:169], v[18:19]
	v_pk_mul_f32 v[18:19], v[148:149], v[168:169]
	v_rcp_f32_e32 v106, v106
	v_rcp_f32_e32 v107, v107
	v_pk_fma_f32 v[18:19], v[108:109], v[152:153], v[18:19]
	v_pk_mul_f32 v[26:27], v[144:145], v[26:27]
	v_pk_fma_f32 v[18:19], v[140:141], v[172:173], v[18:19]
	v_pk_mul_f32 v[28:29], v[142:143], v[28:29]
	v_pk_mul_f32 v[108:109], v[160:161], v[18:19]
	v_pk_mul_f32 v[18:19], v[158:159], v[20:21]
	v_mul_f32_e32 v20, 0xbfb8aa3b, v160
	v_mul_f32_e32 v21, 0xbfb8aa3b, v161
	v_pk_mul_f32 v[18:19], v[106:107], v[18:19]
	v_exp_f32_e32 v20, v20
	v_exp_f32_e32 v21, v21
	v_mul_f32_e32 v106, 0xbfb8aa3b, v192
	v_mul_f32_e32 v107, 0xbfb8aa3b, v193
	v_exp_f32_e32 v106, v106
	v_exp_f32_e32 v107, v107
	v_add_f32_e32 v20, 1.0, v20
	v_add_f32_e32 v21, 1.0, v21
	v_rcp_f32_e32 v20, v20
	v_rcp_f32_e32 v21, v21
	v_add_f32_e32 v106, 1.0, v106
	v_add_f32_e32 v107, 1.0, v107
	v_rcp_f32_e32 v106, v106
	v_rcp_f32_e32 v107, v107
	v_pk_mul_f32 v[20:21], v[20:21], v[108:109]
	v_pk_mul_f32 v[108:109], v[190:191], v[22:23]
	v_pk_mul_f32 v[22:23], v[192:193], v[24:25]
	v_pk_mul_f32 v[30:31], v[136:137], v[30:31]
	v_pk_mul_f32 v[22:23], v[106:107], v[22:23]
	v_mul_f32_e32 v106, 0xbfb8aa3b, v144
	v_mul_f32_e32 v107, 0xbfb8aa3b, v145
	v_exp_f32_e32 v106, v106
	v_exp_f32_e32 v107, v107
	v_mul_f32_e32 v24, 0xbfb8aa3b, v190
	v_mul_f32_e32 v25, 0xbfb8aa3b, v191
	v_add_f32_e32 v106, 1.0, v106
	v_add_f32_e32 v107, 1.0, v107
	v_rcp_f32_e32 v106, v106
	v_rcp_f32_e32 v107, v107
	v_pk_mul_f32 v[32:33], v[134:135], v[32:33]
	v_exp_f32_e32 v24, v24
	v_exp_f32_e32 v25, v25
	v_pk_mul_f32 v[26:27], v[106:107], v[26:27]
	v_mul_f32_e32 v106, 0xbfb8aa3b, v142
	v_mul_f32_e32 v107, 0xbfb8aa3b, v143
	v_exp_f32_e32 v106, v106
	v_exp_f32_e32 v107, v107
	v_add_f32_e32 v24, 1.0, v24
	v_add_f32_e32 v25, 1.0, v25
	v_add_f32_e32 v106, 1.0, v106
	v_add_f32_e32 v107, 1.0, v107
	v_rcp_f32_e32 v106, v106
	v_rcp_f32_e32 v107, v107
	v_rcp_f32_e32 v24, v24
	v_rcp_f32_e32 v25, v25
	v_pk_mul_f32 v[104:105], v[52:53], v[104:105]
	v_pk_mul_f32 v[28:29], v[106:107], v[28:29]
	v_mul_f32_e32 v106, 0xbfb8aa3b, v136
	v_mul_f32_e32 v107, 0xbfb8aa3b, v137
	v_exp_f32_e32 v106, v106
	v_exp_f32_e32 v107, v107
	v_pk_mul_f32 v[24:25], v[24:25], v[108:109]
	v_pk_mul_f32 v[108:109], v[36:37], v[132:133]
	v_add_f32_e32 v106, 1.0, v106
	v_add_f32_e32 v107, 1.0, v107
	v_rcp_f32_e32 v106, v106
	v_rcp_f32_e32 v107, v107
	v_mul_f32_e32 v36, 0xbfb8aa3b, v36
	v_mul_f32_e32 v37, 0xbfb8aa3b, v37
	v_exp_f32_e32 v36, v36
	v_pk_mul_f32 v[30:31], v[106:107], v[30:31]
	v_mul_f32_e32 v106, 0xbfb8aa3b, v134
	v_mul_f32_e32 v107, 0xbfb8aa3b, v135
	v_exp_f32_e32 v106, v106
	v_exp_f32_e32 v107, v107
	v_exp_f32_e32 v37, v37
	v_mul_f32_e32 v52, 0xbfb8aa3b, v52
	v_add_f32_e32 v106, 1.0, v106
	v_add_f32_e32 v107, 1.0, v107
	v_rcp_f32_e32 v106, v106
	v_rcp_f32_e32 v107, v107
	v_mul_f32_e32 v53, 0xbfb8aa3b, v53
	v_exp_f32_e32 v52, v52
	v_exp_f32_e32 v53, v53
	v_pk_mul_f32 v[32:33], v[106:107], v[32:33]
	v_mul_f32_e32 v106, 0xbfb8aa3b, v34
	v_mul_f32_e32 v107, 0xbfb8aa3b, v35
	v_exp_f32_e32 v106, v106
	v_exp_f32_e32 v107, v107
	v_pk_mul_f32 v[34:35], v[34:35], v[130:131]
	v_add_f32_e32 v36, 1.0, v36
	v_add_f32_e32 v106, 1.0, v106
	v_add_f32_e32 v107, 1.0, v107
	v_rcp_f32_e32 v106, v106
	v_rcp_f32_e32 v107, v107
	v_add_f32_e32 v37, 1.0, v37
	v_rcp_f32_e32 v36, v36
	v_rcp_f32_e32 v37, v37
	v_pk_mul_f32 v[34:35], v[106:107], v[34:35]
	v_mul_f32_e32 v106, 0xbfb8aa3b, v38
	v_mul_f32_e32 v107, 0xbfb8aa3b, v39
	v_exp_f32_e32 v106, v106
	v_exp_f32_e32 v107, v107
	v_add_f32_e32 v52, 1.0, v52
	v_add_f32_e32 v53, 1.0, v53
	v_add_f32_e32 v106, 1.0, v106
	v_add_f32_e32 v107, 1.0, v107
	v_rcp_f32_e32 v106, v106
	v_rcp_f32_e32 v107, v107
	v_rcp_f32_e32 v52, v52
	v_rcp_f32_e32 v53, v53
	v_pk_mul_f32 v[36:37], v[36:37], v[108:109]
	v_pk_mul_f32 v[108:109], v[40:41], v[120:121]
	v_pk_mul_f32 v[38:39], v[38:39], v[118:119]
	v_mul_f32_e32 v40, 0xbfb8aa3b, v40
	v_mul_f32_e32 v41, 0xbfb8aa3b, v41
	v_pk_mul_f32 v[38:39], v[106:107], v[38:39]
	v_exp_f32_e32 v40, v40
	v_exp_f32_e32 v41, v41
	v_mul_f32_e32 v106, 0xbfb8aa3b, v50
	v_mul_f32_e32 v107, 0xbfb8aa3b, v51
	v_pk_mul_f32 v[50:51], v[50:51], v[102:103]
	v_pk_mul_f32 v[52:53], v[52:53], v[104:105]
	v_mul_f32_e32 v102, 0xbfb8aa3b, v54
	v_mul_f32_e32 v103, 0xbfb8aa3b, v55
	v_pk_mul_f32 v[104:105], v[56:57], v[116:117]
	v_mul_f32_e32 v56, 0xbfb8aa3b, v56
	v_mul_f32_e32 v57, 0xbfb8aa3b, v57
	v_exp_f32_e32 v102, v102
	v_exp_f32_e32 v103, v103
	v_exp_f32_e32 v56, v56
	v_exp_f32_e32 v57, v57
	v_exp_f32_e32 v106, v106
	v_exp_f32_e32 v107, v107
	v_add_f32_e32 v40, 1.0, v40
	v_add_f32_e32 v41, 1.0, v41
	v_rcp_f32_e32 v40, v40
	v_rcp_f32_e32 v41, v41
	v_add_f32_e32 v102, 1.0, v102
	v_add_f32_e32 v103, 1.0, v103
	v_add_f32_e32 v56, 1.0, v56
	v_add_f32_e32 v57, 1.0, v57
	v_rcp_f32_e32 v102, v102
	v_rcp_f32_e32 v103, v103
	v_rcp_f32_e32 v56, v56
	v_rcp_f32_e32 v57, v57
	v_add_f32_e32 v106, 1.0, v106
	v_add_f32_e32 v107, 1.0, v107
	v_rcp_f32_e32 v106, v106
	v_rcp_f32_e32 v107, v107
	v_pk_mul_f32 v[40:41], v[40:41], v[108:109]
	v_pk_mul_f32 v[54:55], v[54:55], v[114:115]
	v_pk_mul_f32 v[108:109], v[2:3], v[238:239] op_sel_hi:[1,0]
	s_waitcnt vmcnt(0)
	v_pk_mul_f32 v[2:3], v[76:77], v[92:93]
	v_pk_mul_f32 v[54:55], v[102:103], v[54:55]
	v_pk_mul_f32 v[56:57], v[56:57], v[104:105]
	v_pk_mul_f32 v[102:103], v[10:11], v[242:243] op_sel_hi:[1,0]
	v_pk_mul_f32 v[104:105], v[4:5], v[238:239] op_sel_hi:[1,0]
	v_pk_mul_f32 v[4:5], v[74:75], v[90:91]
	v_pk_fma_f32 v[10:11], v[84:85], v[88:89], v[2:3]
	v_pk_fma_f32 v[2:3], v[82:83], v[86:87], v[4:5]
	v_pk_fma_f32 v[4:5], v[104:105], v[80:81], v[10:11]
	v_pk_mul_f32 v[10:11], v[84:85], v[92:93]
	v_pk_mul_f32 v[50:51], v[106:107], v[50:51]
	v_pk_mul_f32 v[106:107], v[14:15], v[240:241] op_sel_hi:[1,0]
	v_pk_mul_f32 v[8:9], v[8:9], v[236:237] op_sel_hi:[1,0]
	v_pk_mul_f32 v[14:15], v[82:83], v[90:91]
	v_pk_fma_f32 v[74:75], v[104:105], v[88:89], v[10:11]
	v_pk_mul_f32 v[76:77], v[104:105], v[92:93]
	v_pk_mul_f32 v[12:13], v[12:13], v[242:243] op_sel_hi:[1,0]
	v_pk_fma_f32 v[10:11], v[108:109], v[86:87], v[14:15]
	v_pk_fma_f32 v[14:15], v[8:9], v[80:81], v[74:75]
	v_pk_fma_f32 v[76:77], v[8:9], v[88:89], v[76:77]
	v_pk_mul_f32 v[8:9], v[8:9], v[92:93]
	v_pk_mul_f32 v[6:7], v[6:7], v[236:237] op_sel_hi:[1,0]
	v_pk_fma_f32 v[8:9], v[12:13], v[88:89], v[8:9]
	v_pk_mul_f32 v[74:75], v[108:109], v[90:91]
	v_pk_fma_f32 v[84:85], v[16:17], v[80:81], v[8:9]
	v_pk_mul_f32 v[8:9], v[12:13], v[92:93]
	v_pk_fma_f32 v[10:11], v[6:7], v[78:79], v[10:11]
	v_pk_fma_f32 v[74:75], v[6:7], v[86:87], v[74:75]
	v_pk_mul_f32 v[6:7], v[6:7], v[90:91]
	v_pk_fma_f32 v[8:9], v[16:17], v[88:89], v[8:9]
	v_pk_fma_f32 v[6:7], v[102:103], v[86:87], v[6:7]
	v_pk_fma_f32 v[104:105], v[48:49], v[80:81], v[8:9]
	v_pk_mul_f32 v[8:9], v[16:17], v[92:93]
	v_pk_fma_f32 v[82:83], v[106:107], v[78:79], v[6:7]
	v_pk_mul_f32 v[6:7], v[102:103], v[90:91]
	v_pk_fma_f32 v[8:9], v[48:49], v[88:89], v[8:9]
	v_pk_fma_f32 v[2:3], v[108:109], v[78:79], v[2:3]
	v_pk_fma_f32 v[6:7], v[106:107], v[86:87], v[6:7]
	v_pk_fma_f32 v[108:109], v[44:45], v[80:81], v[8:9]
	v_pk_mul_f32 v[8:9], v[46:47], v[90:91]
	v_pk_fma_f32 v[74:75], v[102:103], v[78:79], v[74:75]
	v_pk_fma_f32 v[102:103], v[46:47], v[78:79], v[6:7]
	v_pk_mul_f32 v[6:7], v[106:107], v[90:91]
	v_pk_fma_f32 v[8:9], v[42:43], v[86:87], v[8:9]
	v_pk_fma_f32 v[6:7], v[46:47], v[86:87], v[6:7]
	v_pk_fma_f32 v[16:17], v[78:79], v[94:95], v[8:9]
	v_pk_mul_f32 v[8:9], v[86:87], v[94:95]
	v_pk_fma_f32 v[106:107], v[42:43], v[78:79], v[6:7]
	v_pk_fma_f32 v[8:9], v[42:43], v[90:91], v[8:9]
	v_mul_f32_e32 v42, 0xbfb8aa3b, v124
	v_mul_f32_e32 v43, 0xbfb8aa3b, v125
	v_exp_f32_e32 v42, v42
	v_exp_f32_e32 v43, v43
	v_pk_mul_f32 v[6:7], v[48:49], v[92:93]
	v_pk_fma_f32 v[76:77], v[12:13], v[80:81], v[76:77]
	v_pk_fma_f32 v[6:7], v[44:45], v[88:89], v[6:7]
	v_add_f32_e32 v42, 1.0, v42
	v_add_f32_e32 v43, 1.0, v43
	v_pk_fma_f32 v[12:13], v[80:81], v[96:97], v[6:7]
	v_pk_mul_f32 v[6:7], v[88:89], v[96:97]
	v_rcp_f32_e32 v42, v42
	v_rcp_f32_e32 v43, v43
	v_pk_fma_f32 v[6:7], v[44:45], v[92:93], v[6:7]
	v_pk_fma_f32 v[8:9], v[78:79], v[98:99], v[8:9]
	v_pk_fma_f32 v[6:7], v[80:81], v[100:101], v[6:7]
	v_pk_mul_f32 v[46:47], v[180:181], v[106:107]
	v_pk_mul_f32 v[44:45], v[122:123], v[6:7]
	v_pk_mul_f32 v[6:7], v[124:125], v[8:9]
	v_mul_f32_e32 v8, 0xbfb8aa3b, v122
	v_mul_f32_e32 v9, 0xbfb8aa3b, v123
	v_pk_mul_f32 v[6:7], v[42:43], v[6:7]
	v_exp_f32_e32 v8, v8
	v_exp_f32_e32 v9, v9
	v_mul_f32_e32 v42, 0xbfb8aa3b, v128
	v_mul_f32_e32 v43, 0xbfb8aa3b, v129
	v_exp_f32_e32 v42, v42
	v_exp_f32_e32 v43, v43
	v_add_f32_e32 v8, 1.0, v8
	v_add_f32_e32 v9, 1.0, v9
	v_rcp_f32_e32 v8, v8
	v_rcp_f32_e32 v9, v9
	v_add_f32_e32 v42, 1.0, v42
	v_add_f32_e32 v43, 1.0, v43
	v_rcp_f32_e32 v42, v42
	v_rcp_f32_e32 v43, v43
	v_pk_mul_f32 v[8:9], v[8:9], v[44:45]
	v_pk_mul_f32 v[44:45], v[126:127], v[12:13]
	v_pk_mul_f32 v[12:13], v[128:129], v[16:17]
	v_mul_f32_e32 v16, 0xbfb8aa3b, v126
	v_pk_mul_f32 v[12:13], v[42:43], v[12:13]
	v_mul_f32_e32 v42, 0xbfb8aa3b, v180
	v_mul_f32_e32 v43, 0xbfb8aa3b, v181
	v_exp_f32_e32 v42, v42
	v_exp_f32_e32 v43, v43
	v_mul_f32_e32 v17, 0xbfb8aa3b, v127
	v_exp_f32_e32 v16, v16
	v_add_f32_e32 v42, 1.0, v42
	v_add_f32_e32 v43, 1.0, v43
	v_rcp_f32_e32 v42, v42
	v_rcp_f32_e32 v43, v43
	v_exp_f32_e32 v17, v17
	v_add_f32_e32 v16, 1.0, v16
	v_pk_mul_f32 v[14:15], v[62:63], v[14:15]
	v_pk_mul_f32 v[42:43], v[42:43], v[46:47]
	v_mul_f32_e32 v46, 0xbfb8aa3b, v178
	v_mul_f32_e32 v47, 0xbfb8aa3b, v179
	v_exp_f32_e32 v46, v46
	v_exp_f32_e32 v47, v47
	v_add_f32_e32 v17, 1.0, v17
	v_mul_f32_e32 v62, 0xbfb8aa3b, v62
	v_mul_f32_e32 v63, 0xbfb8aa3b, v63
	v_rcp_f32_e32 v16, v16
	v_rcp_f32_e32 v17, v17
	v_add_f32_e32 v46, 1.0, v46
	v_add_f32_e32 v47, 1.0, v47
	v_exp_f32_e32 v62, v62
	v_exp_f32_e32 v63, v63
	v_rcp_f32_e32 v46, v46
	v_rcp_f32_e32 v47, v47
	v_pk_mul_f32 v[16:17], v[16:17], v[44:45]
	v_pk_mul_f32 v[44:45], v[178:179], v[108:109]
	v_add_f32_e32 v62, 1.0, v62
	v_add_f32_e32 v63, 1.0, v63
	v_pk_mul_f32 v[44:45], v[46:47], v[44:45]
	v_mul_f32_e32 v46, 0xbfb8aa3b, v156
	v_mul_f32_e32 v47, 0xbfb8aa3b, v157
	v_rcp_f32_e32 v62, v62
	v_rcp_f32_e32 v63, v63
	v_exp_f32_e32 v46, v46
	v_exp_f32_e32 v47, v47
	v_pk_mul_f32 v[78:79], v[156:157], v[102:103]
	v_pk_mul_f32 v[14:15], v[62:63], v[14:15]
	v_mul_f32_e32 v62, 0xbfb8aa3b, v60
	v_mul_f32_e32 v63, 0xbfb8aa3b, v61
	v_add_f32_e32 v46, 1.0, v46
	v_add_f32_e32 v47, 1.0, v47
	v_exp_f32_e32 v62, v62
	v_exp_f32_e32 v63, v63
	v_rcp_f32_e32 v46, v46
	v_rcp_f32_e32 v47, v47
	v_add_f32_e32 v62, 1.0, v62
	v_add_f32_e32 v63, 1.0, v63
	v_rcp_f32_e32 v62, v62
	v_pk_mul_f32 v[46:47], v[46:47], v[78:79]
	v_mul_f32_e32 v78, 0xbfb8aa3b, v154
	v_mul_f32_e32 v79, 0xbfb8aa3b, v155
	v_rcp_f32_e32 v63, v63
	v_exp_f32_e32 v78, v78
	v_exp_f32_e32 v79, v79
	v_pk_mul_f32 v[2:3], v[60:61], v[2:3]
	v_pk_mul_f32 v[48:49], v[154:155], v[104:105]
	v_pk_mul_f32 v[60:61], v[62:63], v[2:3]
	v_mul_f32_e32 v2, 0xbfb8aa3b, v58
	v_mul_f32_e32 v3, 0xbfb8aa3b, v59
	v_add_f32_e32 v78, 1.0, v78
	v_add_f32_e32 v79, 1.0, v79
	v_exp_f32_e32 v2, v2
	v_exp_f32_e32 v3, v3
	v_rcp_f32_e32 v78, v78
	v_rcp_f32_e32 v79, v79
	v_add_f32_e32 v2, 1.0, v2
	v_add_f32_e32 v3, 1.0, v3
	v_rcp_f32_e32 v2, v2
	v_pk_mul_f32 v[48:49], v[78:79], v[48:49]
	v_mul_f32_e32 v78, 0xbfb8aa3b, v72
	v_mul_f32_e32 v79, 0xbfb8aa3b, v73
	v_rcp_f32_e32 v3, v3
	v_exp_f32_e32 v78, v78
	v_exp_f32_e32 v79, v79
	v_pk_mul_f32 v[4:5], v[58:59], v[4:5]
	v_pk_mul_f32 v[80:81], v[70:71], v[84:85]
	v_pk_mul_f32 v[58:59], v[2:3], v[4:5]
	v_cvt_pk_bf16_f32 v4, v6, v7
	v_lshrrev_b32_e32 v130, 2, v213
	v_and_b32_e32 v131, 3, v213
	v_lshlrev_b32_e32 v134, 6, v131
	v_lshl_add_u32 v134, v130, 2, v134
	v_sub_u32_e32 v135, v130, v249
	v_lshl_add_u32 v135, v135, 3, v232
	v_sub_u32_e32 v136, v131, v250
	v_lshl_add_u32 v132, v136, 3, v234
	v_mov_b32_e32 v133, v235
	v_lshlrev_b64 v[132:133], 1, v[132:133]
	v_mov_b64_e32 v[6:7], s[46:47]
	v_add_f32_e32 v78, 1.0, v78
	v_add_f32_e32 v79, 1.0, v79
	v_cvt_pk_bf16_f32 v2, v18, v19
	v_cvt_pk_bf16_f32 v5, v8, v9
	v_mad_i64_i32 v[8:9], s[4:5], v135, s92, v[6:7]
	v_lshlrev_b64 v[18:19], 1, v[234:235]
	v_rcp_f32_e32 v78, v78
	v_rcp_f32_e32 v79, v79
	v_cvt_pk_bf16_f32 v3, v20, v21
	v_lshl_add_u64 v[8:9], v[8:9], 0, v[132:133]
	v_mul_f32_e32 v70, 0xbfb8aa3b, v70
	v_mul_f32_e32 v71, 0xbfb8aa3b, v71
	ds_bpermute_b32 v138, v134, v2
	ds_bpermute_b32 v139, v134, v3
	ds_bpermute_b32 v140, v134, v4
	ds_bpermute_b32 v141, v134, v5
	v_mov_b64_e32 v[146:147], v[8:9]
	v_or_b32_e32 v8, 1, v135
	v_exp_f32_e32 v70, v70
	v_exp_f32_e32 v71, v71
	v_mad_i64_i32 v[8:9], s[4:5], v8, s92, v[6:7]
	v_pk_mul_f32 v[72:73], v[72:73], v[82:83]
	v_cvt_pk_bf16_f32 v2, v22, v23
	v_cvt_pk_bf16_f32 v3, v24, v25
	v_cvt_pk_bf16_f32 v4, v12, v13
	v_cvt_pk_bf16_f32 v5, v16, v17
	v_lshl_add_u64 v[8:9], v[8:9], 0, v[132:133]
	v_pk_mul_f32 v[72:73], v[78:79], v[72:73]
	v_mul_f32_e32 v78, 0xbfb8aa3b, v68
	v_mul_f32_e32 v79, 0xbfb8aa3b, v69
	v_pk_mul_f32 v[76:77], v[66:67], v[76:77]
	v_mul_f32_e32 v66, 0xbfb8aa3b, v66
	v_mul_f32_e32 v67, 0xbfb8aa3b, v67
	ds_bpermute_b32 v142, v134, v2
	ds_bpermute_b32 v143, v134, v3
	ds_bpermute_b32 v144, v134, v4
	ds_bpermute_b32 v145, v134, v5
	v_mov_b64_e32 v[148:149], v[8:9]
	s_waitcnt lgkmcnt(4)
	global_store_dwordx4 v[146:147], v[138:141], off
	v_or_b32_e32 v8, 2, v135
	v_exp_f32_e32 v78, v78
	v_exp_f32_e32 v79, v79
	v_exp_f32_e32 v66, v66
	v_exp_f32_e32 v67, v67
	v_mad_i64_i32 v[8:9], s[4:5], v8, s92, v[6:7]
	v_add_f32_e32 v70, 1.0, v70
	v_add_f32_e32 v71, 1.0, v71
	v_cvt_pk_bf16_f32 v2, v26, v27
	v_cvt_pk_bf16_f32 v3, v28, v29
	v_cvt_pk_bf16_f32 v4, v42, v43
	v_cvt_pk_bf16_f32 v5, v44, v45
	v_lshl_add_u64 v[8:9], v[8:9], 0, v[132:133]
	v_rcp_f32_e32 v70, v70
	v_rcp_f32_e32 v71, v71
	v_pk_mul_f32 v[68:69], v[68:69], v[74:75]
	v_mul_f32_e32 v74, 0xbfb8aa3b, v64
	v_mul_f32_e32 v75, 0xbfb8aa3b, v65
	ds_bpermute_b32 v138, v134, v2
	ds_bpermute_b32 v139, v134, v3
	ds_bpermute_b32 v140, v134, v4
	ds_bpermute_b32 v141, v134, v5
	v_mov_b64_e32 v[146:147], v[8:9]
	s_waitcnt lgkmcnt(4)
	global_store_dwordx4 v[148:149], v[142:145], off
	v_or_b32_e32 v8, 3, v135
	v_exp_f32_e32 v74, v74
	v_exp_f32_e32 v75, v75
	v_mad_i64_i32 v[8:9], s[4:5], v8, s92, v[6:7]
	v_add_f32_e32 v78, 1.0, v78
	v_add_f32_e32 v79, 1.0, v79
	v_add_f32_e32 v66, 1.0, v66
	v_add_f32_e32 v67, 1.0, v67
	v_cvt_pk_bf16_f32 v2, v30, v31
	v_cvt_pk_bf16_f32 v3, v32, v33
	v_cvt_pk_bf16_f32 v4, v46, v47
	v_cvt_pk_bf16_f32 v5, v48, v49
	v_lshl_add_u64 v[8:9], v[8:9], 0, v[132:133]
	v_rcp_f32_e32 v78, v78
	v_rcp_f32_e32 v79, v79
	v_rcp_f32_e32 v66, v66
	v_rcp_f32_e32 v67, v67
	ds_bpermute_b32 v142, v134, v2
	ds_bpermute_b32 v143, v134, v3
	ds_bpermute_b32 v144, v134, v4
	ds_bpermute_b32 v145, v134, v5
	v_mov_b64_e32 v[148:149], v[8:9]
	s_waitcnt lgkmcnt(4)
	global_store_dwordx4 v[146:147], v[138:141], off
	v_or_b32_e32 v8, 4, v135
	v_pk_mul_f32 v[70:71], v[70:71], v[80:81]
	v_mad_i64_i32 v[8:9], s[4:5], v8, s92, v[6:7]
	v_add_f32_e32 v74, 1.0, v74
	v_add_f32_e32 v75, 1.0, v75
	v_cvt_pk_bf16_f32 v2, v34, v35
	v_cvt_pk_bf16_f32 v3, v36, v37
	v_cvt_pk_bf16_f32 v4, v72, v73
	v_cvt_pk_bf16_f32 v5, v70, v71
	v_lshl_add_u64 v[8:9], v[8:9], 0, v[132:133]
	v_rcp_f32_e32 v74, v74
	v_rcp_f32_e32 v75, v75
	ds_bpermute_b32 v138, v134, v2
	ds_bpermute_b32 v139, v134, v3
	ds_bpermute_b32 v140, v134, v4
	ds_bpermute_b32 v141, v134, v5
	v_mov_b64_e32 v[146:147], v[8:9]
	s_waitcnt lgkmcnt(4)
	global_store_dwordx4 v[148:149], v[142:145], off
	v_or_b32_e32 v8, 5, v135
	v_pk_mul_f32 v[68:69], v[78:79], v[68:69]
	v_pk_mul_f32 v[66:67], v[66:67], v[76:77]
	v_mad_i64_i32 v[8:9], s[4:5], v8, s92, v[6:7]
	v_cvt_pk_bf16_f32 v2, v38, v39
	v_cvt_pk_bf16_f32 v3, v40, v41
	v_cvt_pk_bf16_f32 v4, v68, v69
	v_cvt_pk_bf16_f32 v5, v66, v67
	v_lshl_add_u64 v[8:9], v[8:9], 0, v[132:133]
	v_pk_mul_f32 v[10:11], v[64:65], v[10:11]
	ds_bpermute_b32 v142, v134, v2
	ds_bpermute_b32 v143, v134, v3
	ds_bpermute_b32 v144, v134, v4
	ds_bpermute_b32 v145, v134, v5
	v_mov_b64_e32 v[148:149], v[8:9]
	s_waitcnt lgkmcnt(4)
	global_store_dwordx4 v[146:147], v[138:141], off
	v_or_b32_e32 v8, 6, v135
	v_pk_mul_f32 v[10:11], v[74:75], v[10:11]
	v_mad_i64_i32 v[8:9], s[4:5], v8, s92, v[6:7]
	v_cvt_pk_bf16_f32 v2, v50, v51
	v_cvt_pk_bf16_f32 v3, v52, v53
	v_cvt_pk_bf16_f32 v4, v10, v11
	v_cvt_pk_bf16_f32 v5, v14, v15
	v_lshl_add_u64 v[8:9], v[8:9], 0, v[132:133]
	ds_bpermute_b32 v138, v134, v2
	ds_bpermute_b32 v139, v134, v3
	ds_bpermute_b32 v140, v134, v4
	ds_bpermute_b32 v141, v134, v5
	v_mov_b64_e32 v[146:147], v[8:9]
	s_waitcnt lgkmcnt(4)
	global_store_dwordx4 v[148:149], v[142:145], off
	v_or_b32_e32 v8, 7, v135
	v_mad_i64_i32 v[6:7], s[4:5], v8, s92, v[6:7]
	v_cvt_pk_bf16_f32 v2, v54, v55
	v_cvt_pk_bf16_f32 v3, v56, v57
	v_cvt_pk_bf16_f32 v4, v60, v61
	v_cvt_pk_bf16_f32 v5, v58, v59
	v_lshl_add_u64 v[6:7], v[6:7], 0, v[132:133]
	ds_bpermute_b32 v142, v134, v2
	ds_bpermute_b32 v143, v134, v3
	ds_bpermute_b32 v144, v134, v4
	ds_bpermute_b32 v145, v134, v5
	v_mov_b64_e32 v[148:149], v[6:7]
	s_waitcnt lgkmcnt(4)
	global_store_dwordx4 v[146:147], v[138:141], off
	s_andn2_b64 vcc, exec, s[40:41]
	s_waitcnt lgkmcnt(0)
	global_store_dwordx4 v[148:149], v[142:145], off
	s_cbranch_vccnz .LBB0_386
	s_andn2_b64 vcc, exec, s[24:25]
	s_cbranch_vccnz .LBB0_385
	s_barrier
	s_branch .LBB0_385
